# projection epilogue of the hyena-column tiles: wave-private LDS transpose so every HYT store instruction writes 8 complete 128-byte lines (was 32 pieces of 32 bytes)
# speedup vs baseline: 1.1916x; 1.0073x over previous
.LBB0_362:
	s_andn2_b64 vcc, exec, s[20:21]
	s_cbranch_vccnz .LBB0_364
	v_ashrrev_i32_e32 v161, 2, v166
	v_or_b32_e32 v160, s18, v168
	v_and_b32_e32 v161, 0xfffff800, v161
	v_add3_u32 v168, v160, v199, v161
	v_add_u32_e32 v162, 0xfffff800, v168
	v_and_b32_e32 v164, 0x1f80, v166
	v_ashrrev_i32_e32 v163, 31, v162
	v_lshlrev_b64 v[162:163], 14, v[162:163]
	v_lshlrev_b32_e32 v164, 1, v164
	v_lshl_add_u64 v[162:163], s[0:1], 0, v[162:163]
	v_lshl_or_b32 v164, v200, 4, v164
	v_lshl_add_u64 v[162:163], v[162:163], 0, v[164:165]
	v_add_u32_e32 v168, 0xfffff820, v168
	v_ashrrev_i32_e32 v169, 31, v168
	v_lshlrev_b64 v[168:169], 14, v[168:169]
	v_lshl_add_u64 v[168:169], s[0:1], 0, v[168:169]
	v_lshl_add_u64 v[168:169], v[168:169], 0, v[164:165]
	v_and_b32_e32 v255, 63, v214
	v_lshrrev_b32_e32 v221, 6, v214
	v_lshlrev_b32_e32 v221, 13, v221
	v_add_u32_e32 v221, 0x10010, v221
	v_lshrrev_b32_e32 v253, 3, v255
	v_and_b32_e32 v254, 7, v255
	v_xor_b32_e32 v244, v253, v254
	v_lshlrev_b32_e32 v254, 4, v254
	v_lshl_or_b32 v254, v253, 14, v254
	v_lshlrev_b32_e32 v253, 8, v253
	v_lshl_or_b32 v253, v244, 4, v253
	v_add_u32_e32 v253, v221, v253
	v_and_b32_e32 v244, 15, v255
	v_lshrrev_b32_e32 v245, 5, v255
	v_xor_b32_e32 v245, v244, v245
	v_and_b32_e32 v255, 31, v255
	v_lshl_add_u32 v255, v255, 8, v221
	v_mov_b32_e32 v221, v245
	v_lshl_add_u32 v244, v221, 4, v255
	v_xor_b32_e32 v245, 2, v221
	v_lshl_add_u32 v245, v245, 4, v255
	v_xor_b32_e32 v246, 4, v221
	v_lshl_add_u32 v246, v246, 4, v255
	v_xor_b32_e32 v247, 6, v221
	v_lshl_add_u32 v247, v247, 4, v255
	v_xor_b32_e32 v248, 8, v221
	v_lshl_add_u32 v248, v248, 4, v255
	v_xor_b32_e32 v249, 10, v221
	v_lshl_add_u32 v249, v249, 4, v255
	v_xor_b32_e32 v250, 12, v221
	v_lshl_add_u32 v250, v250, 4, v255
	v_xor_b32_e32 v251, 14, v221
	v_lshl_add_u32 v251, v251, 4, v255
	v_readfirstlane_b32 s100, v162
	v_readfirstlane_b32 s101, v163
	v_cvt_pk_bf16_f32 v228, v112, v113
	v_cvt_pk_bf16_f32 v229, v114, v115
	v_cvt_pk_bf16_f32 v230, v116, v117
	v_cvt_pk_bf16_f32 v231, v118, v119
	s_nop 1
	v_permlane32_swap_b32_e32 v228, v230
	v_permlane32_swap_b32_e32 v229, v231
	ds_write_b128 v244, v[228:231]
	v_cvt_pk_bf16_f32 v232, v120, v121
	v_cvt_pk_bf16_f32 v233, v122, v123
	v_cvt_pk_bf16_f32 v234, v124, v125
	v_cvt_pk_bf16_f32 v235, v126, v127
	s_nop 1
	v_permlane32_swap_b32_e32 v232, v234
	v_permlane32_swap_b32_e32 v233, v235
	ds_write_b128 v245, v[232:235]
	v_cvt_pk_bf16_f32 v236, v80, v81
	v_cvt_pk_bf16_f32 v237, v82, v83
	v_cvt_pk_bf16_f32 v238, v84, v85
	v_cvt_pk_bf16_f32 v239, v86, v87
	s_nop 1
	v_permlane32_swap_b32_e32 v236, v238
	v_permlane32_swap_b32_e32 v237, v239
	ds_write_b128 v246, v[236:239]
	v_cvt_pk_bf16_f32 v240, v88, v89
	v_cvt_pk_bf16_f32 v241, v90, v91
	v_cvt_pk_bf16_f32 v242, v92, v93
	v_cvt_pk_bf16_f32 v243, v94, v95
	s_nop 1
	v_permlane32_swap_b32_e32 v240, v242
	v_permlane32_swap_b32_e32 v241, v243
	ds_write_b128 v247, v[240:243]
	v_cvt_pk_bf16_f32 v228, v48, v49
	v_cvt_pk_bf16_f32 v229, v50, v51
	v_cvt_pk_bf16_f32 v230, v52, v53
	v_cvt_pk_bf16_f32 v231, v54, v55
	s_nop 1
	v_permlane32_swap_b32_e32 v228, v230
	v_permlane32_swap_b32_e32 v229, v231
	ds_write_b128 v248, v[228:231]
	v_cvt_pk_bf16_f32 v232, v56, v57
	v_cvt_pk_bf16_f32 v233, v58, v59
	v_cvt_pk_bf16_f32 v234, v60, v61
	v_cvt_pk_bf16_f32 v235, v62, v63
	s_nop 1
	v_permlane32_swap_b32_e32 v232, v234
	v_permlane32_swap_b32_e32 v233, v235
	ds_write_b128 v249, v[232:235]
	v_cvt_pk_bf16_f32 v236, v16, v17
	v_cvt_pk_bf16_f32 v237, v18, v19
	v_cvt_pk_bf16_f32 v238, v20, v21
	v_cvt_pk_bf16_f32 v239, v22, v23
	s_nop 1
	v_permlane32_swap_b32_e32 v236, v238
	v_permlane32_swap_b32_e32 v237, v239
	ds_write_b128 v250, v[236:239]
	v_cvt_pk_bf16_f32 v240, v24, v25
	v_cvt_pk_bf16_f32 v241, v26, v27
	v_cvt_pk_bf16_f32 v242, v28, v29
	v_cvt_pk_bf16_f32 v243, v30, v31
	s_nop 1
	v_permlane32_swap_b32_e32 v240, v242
	v_permlane32_swap_b32_e32 v241, v243
	ds_write_b128 v251, v[240:243]
	s_waitcnt lgkmcnt(0)
	ds_read_b128 v[128:131], v253
	ds_read_b128 v[132:135], v253 offset:128
	ds_read_b128 v[136:139], v253 offset:2176
	ds_read_b128 v[140:143], v253 offset:2048
	ds_read_b128 v[144:147], v253 offset:4096
	ds_read_b128 v[148:151], v253 offset:4224
	ds_read_b128 v[152:155], v253 offset:6272
	ds_read_b128 v[156:159], v253 offset:6144
	v_add_u32_e32 v255, 0x0, v254
	s_waitcnt lgkmcnt(7)
	global_store_dwordx4 v255, v[128:131], s[100:101]
	s_waitcnt lgkmcnt(6)
	global_store_dwordx4 v255, v[132:135], s[100:101] offset:128
	v_add_u32_e32 v255, 0x20000, v254
	s_waitcnt lgkmcnt(5)
	global_store_dwordx4 v255, v[136:139], s[100:101]
	s_waitcnt lgkmcnt(4)
	global_store_dwordx4 v255, v[140:143], s[100:101] offset:128
	v_add_u32_e32 v255, 0x40000, v254
	s_waitcnt lgkmcnt(3)
	global_store_dwordx4 v255, v[144:147], s[100:101]
	s_waitcnt lgkmcnt(2)
	global_store_dwordx4 v255, v[148:151], s[100:101] offset:128
	v_add_u32_e32 v255, 0x60000, v254
	s_waitcnt lgkmcnt(1)
	global_store_dwordx4 v255, v[152:155], s[100:101]
	s_waitcnt lgkmcnt(0)
	global_store_dwordx4 v255, v[156:159], s[100:101] offset:128
	v_readfirstlane_b32 s100, v168
	v_readfirstlane_b32 s101, v169
	v_cvt_pk_bf16_f32 v228, v96, v97
	v_cvt_pk_bf16_f32 v229, v98, v99
	v_cvt_pk_bf16_f32 v230, v100, v101
	v_cvt_pk_bf16_f32 v231, v102, v103
	s_nop 1
	v_permlane32_swap_b32_e32 v228, v230
	v_permlane32_swap_b32_e32 v229, v231
	ds_write_b128 v244, v[228:231]
	v_cvt_pk_bf16_f32 v232, v104, v105
	v_cvt_pk_bf16_f32 v233, v106, v107
	v_cvt_pk_bf16_f32 v234, v108, v109
	v_cvt_pk_bf16_f32 v235, v110, v111
	s_nop 1
	v_permlane32_swap_b32_e32 v232, v234
	v_permlane32_swap_b32_e32 v233, v235
	ds_write_b128 v245, v[232:235]
	v_cvt_pk_bf16_f32 v236, v64, v65
	v_cvt_pk_bf16_f32 v237, v66, v67
	v_cvt_pk_bf16_f32 v238, v68, v69
	v_cvt_pk_bf16_f32 v239, v70, v71
	s_nop 1
	v_permlane32_swap_b32_e32 v236, v238
	v_permlane32_swap_b32_e32 v237, v239
	ds_write_b128 v246, v[236:239]
	v_cvt_pk_bf16_f32 v240, v72, v73
	v_cvt_pk_bf16_f32 v241, v74, v75
	v_cvt_pk_bf16_f32 v242, v76, v77
	v_cvt_pk_bf16_f32 v243, v78, v79
	s_nop 1
	v_permlane32_swap_b32_e32 v240, v242
	v_permlane32_swap_b32_e32 v241, v243
	ds_write_b128 v247, v[240:243]
	v_cvt_pk_bf16_f32 v228, v32, v33
	v_cvt_pk_bf16_f32 v229, v34, v35
	v_cvt_pk_bf16_f32 v230, v36, v37
	v_cvt_pk_bf16_f32 v231, v38, v39
	s_nop 1
	v_permlane32_swap_b32_e32 v228, v230
	v_permlane32_swap_b32_e32 v229, v231
	ds_write_b128 v248, v[228:231]
	v_cvt_pk_bf16_f32 v232, v40, v41
	v_cvt_pk_bf16_f32 v233, v42, v43
	v_cvt_pk_bf16_f32 v234, v44, v45
	v_cvt_pk_bf16_f32 v235, v46, v47
	s_nop 1
	v_permlane32_swap_b32_e32 v232, v234
	v_permlane32_swap_b32_e32 v233, v235
	ds_write_b128 v249, v[232:235]
	v_cvt_pk_bf16_f32 v236, v0, v1
	v_cvt_pk_bf16_f32 v237, v2, v3
	v_cvt_pk_bf16_f32 v238, v4, v5
	v_cvt_pk_bf16_f32 v239, v6, v7
	s_nop 1
	v_permlane32_swap_b32_e32 v236, v238
	v_permlane32_swap_b32_e32 v237, v239
	ds_write_b128 v250, v[236:239]
	v_cvt_pk_bf16_f32 v240, v8, v9
	v_cvt_pk_bf16_f32 v241, v10, v11
	v_cvt_pk_bf16_f32 v242, v12, v13
	v_cvt_pk_bf16_f32 v243, v14, v15
	s_nop 1
	v_permlane32_swap_b32_e32 v240, v242
	v_permlane32_swap_b32_e32 v241, v243
	ds_write_b128 v251, v[240:243]
	s_waitcnt lgkmcnt(0)
	ds_read_b128 v[128:131], v253
	ds_read_b128 v[132:135], v253 offset:128
	ds_read_b128 v[136:139], v253 offset:2176
	ds_read_b128 v[140:143], v253 offset:2048
	ds_read_b128 v[144:147], v253 offset:4096
	ds_read_b128 v[148:151], v253 offset:4224
	ds_read_b128 v[152:155], v253 offset:6272
	ds_read_b128 v[156:159], v253 offset:6144
	v_add_u32_e32 v255, 0x0, v254
	s_waitcnt lgkmcnt(7)
	global_store_dwordx4 v255, v[128:131], s[100:101]
	s_waitcnt lgkmcnt(6)
	global_store_dwordx4 v255, v[132:135], s[100:101] offset:128
	v_add_u32_e32 v255, 0x20000, v254
	s_waitcnt lgkmcnt(5)
	global_store_dwordx4 v255, v[136:139], s[100:101]
	s_waitcnt lgkmcnt(4)
	global_store_dwordx4 v255, v[140:143], s[100:101] offset:128
	v_add_u32_e32 v255, 0x40000, v254
	s_waitcnt lgkmcnt(3)
	global_store_dwordx4 v255, v[144:147], s[100:101]
	s_waitcnt lgkmcnt(2)
	global_store_dwordx4 v255, v[148:151], s[100:101] offset:128
	v_add_u32_e32 v255, 0x60000, v254
	s_waitcnt lgkmcnt(1)
	global_store_dwordx4 v255, v[152:155], s[100:101]
	s_waitcnt lgkmcnt(0)
	global_store_dwordx4 v255, v[156:159], s[100:101] offset:128

.LBB0_745:
	s_andn2_b64 vcc, exec, s[14:15]
	s_cbranch_vccnz .LBB0_747
	v_ashrrev_i32_e32 v161, 2, v166
	v_or_b32_e32 v160, s12, v168
	v_and_b32_e32 v161, 0xfffff800, v161
	v_add3_u32 v168, v160, v199, v161
	v_add_u32_e32 v162, 0xfffff800, v168
	v_and_b32_e32 v164, 0x1f80, v166
	v_ashrrev_i32_e32 v163, 31, v162
	v_lshlrev_b64 v[162:163], 14, v[162:163]
	v_lshlrev_b32_e32 v164, 1, v164
	v_lshl_add_u64 v[162:163], s[0:1], 0, v[162:163]
	v_lshl_or_b32 v164, v200, 4, v164
	v_lshl_add_u64 v[162:163], v[162:163], 0, v[164:165]
	v_add_u32_e32 v168, 0xfffff820, v168
	v_ashrrev_i32_e32 v169, 31, v168
	v_lshlrev_b64 v[168:169], 14, v[168:169]
	v_lshl_add_u64 v[168:169], s[0:1], 0, v[168:169]
	v_lshl_add_u64 v[168:169], v[168:169], 0, v[164:165]
	v_and_b32_e32 v255, 63, v214
	v_lshrrev_b32_e32 v221, 6, v214
	v_lshlrev_b32_e32 v221, 13, v221
	v_add_u32_e32 v221, 0x10010, v221
	v_lshrrev_b32_e32 v253, 3, v255
	v_and_b32_e32 v254, 7, v255
	v_xor_b32_e32 v244, v253, v254
	v_lshlrev_b32_e32 v254, 4, v254
	v_lshl_or_b32 v254, v253, 14, v254
	v_lshlrev_b32_e32 v253, 8, v253
	v_lshl_or_b32 v253, v244, 4, v253
	v_add_u32_e32 v253, v221, v253
	v_and_b32_e32 v244, 15, v255
	v_lshrrev_b32_e32 v245, 5, v255
	v_xor_b32_e32 v245, v244, v245
	v_and_b32_e32 v255, 31, v255
	v_lshl_add_u32 v255, v255, 8, v221
	v_mov_b32_e32 v221, v245
	v_lshl_add_u32 v244, v221, 4, v255
	v_xor_b32_e32 v245, 2, v221
	v_lshl_add_u32 v245, v245, 4, v255
	v_xor_b32_e32 v246, 4, v221
	v_lshl_add_u32 v246, v246, 4, v255
	v_xor_b32_e32 v247, 6, v221
	v_lshl_add_u32 v247, v247, 4, v255
	v_xor_b32_e32 v248, 8, v221
	v_lshl_add_u32 v248, v248, 4, v255
	v_xor_b32_e32 v249, 10, v221
	v_lshl_add_u32 v249, v249, 4, v255
	v_xor_b32_e32 v250, 12, v221
	v_lshl_add_u32 v250, v250, 4, v255
	v_xor_b32_e32 v251, 14, v221
	v_lshl_add_u32 v251, v251, 4, v255
	v_readfirstlane_b32 s100, v162
	v_readfirstlane_b32 s101, v163
	v_cvt_pk_bf16_f32 v228, v112, v113
	v_cvt_pk_bf16_f32 v229, v114, v115
	v_cvt_pk_bf16_f32 v230, v116, v117
	v_cvt_pk_bf16_f32 v231, v118, v119
	s_nop 1
	v_permlane32_swap_b32_e32 v228, v230
	v_permlane32_swap_b32_e32 v229, v231
	ds_write_b128 v244, v[228:231]
	v_cvt_pk_bf16_f32 v232, v120, v121
	v_cvt_pk_bf16_f32 v233, v122, v123
	v_cvt_pk_bf16_f32 v234, v124, v125
	v_cvt_pk_bf16_f32 v235, v126, v127
	s_nop 1
	v_permlane32_swap_b32_e32 v232, v234
	v_permlane32_swap_b32_e32 v233, v235
	ds_write_b128 v245, v[232:235]
	v_cvt_pk_bf16_f32 v236, v80, v81
	v_cvt_pk_bf16_f32 v237, v82, v83
	v_cvt_pk_bf16_f32 v238, v84, v85
	v_cvt_pk_bf16_f32 v239, v86, v87
	s_nop 1
	v_permlane32_swap_b32_e32 v236, v238
	v_permlane32_swap_b32_e32 v237, v239
	ds_write_b128 v246, v[236:239]
	v_cvt_pk_bf16_f32 v240, v88, v89
	v_cvt_pk_bf16_f32 v241, v90, v91
	v_cvt_pk_bf16_f32 v242, v92, v93
	v_cvt_pk_bf16_f32 v243, v94, v95
	s_nop 1
	v_permlane32_swap_b32_e32 v240, v242
	v_permlane32_swap_b32_e32 v241, v243
	ds_write_b128 v247, v[240:243]
	v_cvt_pk_bf16_f32 v228, v48, v49
	v_cvt_pk_bf16_f32 v229, v50, v51
	v_cvt_pk_bf16_f32 v230, v52, v53
	v_cvt_pk_bf16_f32 v231, v54, v55
	s_nop 1
	v_permlane32_swap_b32_e32 v228, v230
	v_permlane32_swap_b32_e32 v229, v231
	ds_write_b128 v248, v[228:231]
	v_cvt_pk_bf16_f32 v232, v56, v57
	v_cvt_pk_bf16_f32 v233, v58, v59
	v_cvt_pk_bf16_f32 v234, v60, v61
	v_cvt_pk_bf16_f32 v235, v62, v63
	s_nop 1
	v_permlane32_swap_b32_e32 v232, v234
	v_permlane32_swap_b32_e32 v233, v235
	ds_write_b128 v249, v[232:235]
	v_cvt_pk_bf16_f32 v236, v16, v17
	v_cvt_pk_bf16_f32 v237, v18, v19
	v_cvt_pk_bf16_f32 v238, v20, v21
	v_cvt_pk_bf16_f32 v239, v22, v23
	s_nop 1
	v_permlane32_swap_b32_e32 v236, v238
	v_permlane32_swap_b32_e32 v237, v239
	ds_write_b128 v250, v[236:239]
	v_cvt_pk_bf16_f32 v240, v24, v25
	v_cvt_pk_bf16_f32 v241, v26, v27
	v_cvt_pk_bf16_f32 v242, v28, v29
	v_cvt_pk_bf16_f32 v243, v30, v31
	s_nop 1
	v_permlane32_swap_b32_e32 v240, v242
	v_permlane32_swap_b32_e32 v241, v243
	ds_write_b128 v251, v[240:243]
	s_waitcnt lgkmcnt(0)
	ds_read_b128 v[128:131], v253
	ds_read_b128 v[132:135], v253 offset:128
	ds_read_b128 v[136:139], v253 offset:2176
	ds_read_b128 v[140:143], v253 offset:2048
	ds_read_b128 v[144:147], v253 offset:4096
	ds_read_b128 v[148:151], v253 offset:4224
	ds_read_b128 v[152:155], v253 offset:6272
	ds_read_b128 v[156:159], v253 offset:6144
	v_add_u32_e32 v255, 0x0, v254
	s_waitcnt lgkmcnt(7)
	global_store_dwordx4 v255, v[128:131], s[100:101]
	s_waitcnt lgkmcnt(6)
	global_store_dwordx4 v255, v[132:135], s[100:101] offset:128
	v_add_u32_e32 v255, 0x20000, v254
	s_waitcnt lgkmcnt(5)
	global_store_dwordx4 v255, v[136:139], s[100:101]
	s_waitcnt lgkmcnt(4)
	global_store_dwordx4 v255, v[140:143], s[100:101] offset:128
	v_add_u32_e32 v255, 0x40000, v254
	s_waitcnt lgkmcnt(3)
	global_store_dwordx4 v255, v[144:147], s[100:101]
	s_waitcnt lgkmcnt(2)
	global_store_dwordx4 v255, v[148:151], s[100:101] offset:128
	v_add_u32_e32 v255, 0x60000, v254
	s_waitcnt lgkmcnt(1)
	global_store_dwordx4 v255, v[152:155], s[100:101]
	s_waitcnt lgkmcnt(0)
	global_store_dwordx4 v255, v[156:159], s[100:101] offset:128
	v_readfirstlane_b32 s100, v168
	v_readfirstlane_b32 s101, v169
	v_cvt_pk_bf16_f32 v228, v96, v97
	v_cvt_pk_bf16_f32 v229, v98, v99
	v_cvt_pk_bf16_f32 v230, v100, v101
	v_cvt_pk_bf16_f32 v231, v102, v103
	s_nop 1
	v_permlane32_swap_b32_e32 v228, v230
	v_permlane32_swap_b32_e32 v229, v231
	ds_write_b128 v244, v[228:231]
	v_cvt_pk_bf16_f32 v232, v104, v105
	v_cvt_pk_bf16_f32 v233, v106, v107
	v_cvt_pk_bf16_f32 v234, v108, v109
	v_cvt_pk_bf16_f32 v235, v110, v111
	s_nop 1
	v_permlane32_swap_b32_e32 v232, v234
	v_permlane32_swap_b32_e32 v233, v235
	ds_write_b128 v245, v[232:235]
	v_cvt_pk_bf16_f32 v236, v64, v65
	v_cvt_pk_bf16_f32 v237, v66, v67
	v_cvt_pk_bf16_f32 v238, v68, v69
	v_cvt_pk_bf16_f32 v239, v70, v71
	s_nop 1
	v_permlane32_swap_b32_e32 v236, v238
	v_permlane32_swap_b32_e32 v237, v239
	ds_write_b128 v246, v[236:239]
	v_cvt_pk_bf16_f32 v240, v72, v73
	v_cvt_pk_bf16_f32 v241, v74, v75
	v_cvt_pk_bf16_f32 v242, v76, v77
	v_cvt_pk_bf16_f32 v243, v78, v79
	s_nop 1
	v_permlane32_swap_b32_e32 v240, v242
	v_permlane32_swap_b32_e32 v241, v243
	ds_write_b128 v247, v[240:243]
	v_cvt_pk_bf16_f32 v228, v32, v33
	v_cvt_pk_bf16_f32 v229, v34, v35
	v_cvt_pk_bf16_f32 v230, v36, v37
	v_cvt_pk_bf16_f32 v231, v38, v39
	s_nop 1
	v_permlane32_swap_b32_e32 v228, v230
	v_permlane32_swap_b32_e32 v229, v231
	ds_write_b128 v248, v[228:231]
	v_cvt_pk_bf16_f32 v232, v40, v41
	v_cvt_pk_bf16_f32 v233, v42, v43
	v_cvt_pk_bf16_f32 v234, v44, v45
	v_cvt_pk_bf16_f32 v235, v46, v47
	s_nop 1
	v_permlane32_swap_b32_e32 v232, v234
	v_permlane32_swap_b32_e32 v233, v235
	ds_write_b128 v249, v[232:235]
	v_cvt_pk_bf16_f32 v236, v0, v1
	v_cvt_pk_bf16_f32 v237, v2, v3
	v_cvt_pk_bf16_f32 v238, v4, v5
	v_cvt_pk_bf16_f32 v239, v6, v7
	s_nop 1
	v_permlane32_swap_b32_e32 v236, v238
	v_permlane32_swap_b32_e32 v237, v239
	ds_write_b128 v250, v[236:239]
	v_cvt_pk_bf16_f32 v240, v8, v9
	v_cvt_pk_bf16_f32 v241, v10, v11
	v_cvt_pk_bf16_f32 v242, v12, v13
	v_cvt_pk_bf16_f32 v243, v14, v15
	s_nop 1
	v_permlane32_swap_b32_e32 v240, v242
	v_permlane32_swap_b32_e32 v241, v243
	ds_write_b128 v251, v[240:243]
	s_waitcnt lgkmcnt(0)
	ds_read_b128 v[128:131], v253
	ds_read_b128 v[132:135], v253 offset:128
	ds_read_b128 v[136:139], v253 offset:2176
	ds_read_b128 v[140:143], v253 offset:2048
	ds_read_b128 v[144:147], v253 offset:4096
	ds_read_b128 v[148:151], v253 offset:4224
	ds_read_b128 v[152:155], v253 offset:6272
	ds_read_b128 v[156:159], v253 offset:6144
	v_add_u32_e32 v255, 0x0, v254
	s_waitcnt lgkmcnt(7)
	global_store_dwordx4 v255, v[128:131], s[100:101]
	s_waitcnt lgkmcnt(6)
	global_store_dwordx4 v255, v[132:135], s[100:101] offset:128
	v_add_u32_e32 v255, 0x20000, v254
	s_waitcnt lgkmcnt(5)
	global_store_dwordx4 v255, v[136:139], s[100:101]
	s_waitcnt lgkmcnt(4)
	global_store_dwordx4 v255, v[140:143], s[100:101] offset:128
	v_add_u32_e32 v255, 0x40000, v254
	s_waitcnt lgkmcnt(3)
	global_store_dwordx4 v255, v[144:147], s[100:101]
	s_waitcnt lgkmcnt(2)
	global_store_dwordx4 v255, v[148:151], s[100:101] offset:128
	v_add_u32_e32 v255, 0x60000, v254
	s_waitcnt lgkmcnt(1)
	global_store_dwordx4 v255, v[152:155], s[100:101]
	s_waitcnt lgkmcnt(0)
	global_store_dwordx4 v255, v[156:159], s[100:101] offset:128
